# stack4 plus general GEMM K-loop first iteration peeled with MFMA srcC=0, accumulator zeroing block (128 v_mov per tile) removed
# speedup vs baseline: 1.0108x; 1.0108x over previous
; #define PG8_STAGE(bufoff, gbase, v0, dv) do { _Pragma("unroll") for (int _i = 0; _i < 2; ++_i) \
;         __builtin_amdgcn_global_load_lds((const unsigned*)((const char*)(gbase) + ((v0) + (unsigned)_i * (dv))), (PG8_LAS unsigned*)(lds + (bufoff) + ldsw + _i * 8192), 16, 0, 0); } while (0)
; #define PG8_LDA(dst, b, h) do { _Pragma("unroll") for (int m = 0; m < 4; ++m) _Pragma("unroll") for (int k = 0; k < 2; ++k) dst[m][k] = *(const PG8_LAS bf16x8*)(lds + PG8_SA(b, h) + aoff + m * 2048 + k * 1024); } while (0)
; #define PG8_LDB(dst, b, h) do { _Pragma("unroll") for (int n = 0; n < 2; ++n) _Pragma("unroll") for (int k = 0; k < 2; ++k) dst[n][k] = *(const PG8_LAS bf16x8*)(lds + PG8_SB(b, h) + boff + n * 2048 + k * 1024); } while (0)
; #define PG8_WAIT_V(n) asm volatile("s_waitcnt vmcnt(" #n ")" ::: "memory")
; #define PG8_WAIT_L(n) asm volatile("s_waitcnt lgkmcnt(" #n ")" ::: "memory")
; #define PG8_BAR __builtin_amdgcn_s_barrier()
; #define PG8_SCHED __builtin_amdgcn_sched_barrier(0)
; template <class Epi, class Sched, bool MERGE>
; __device__ __forceinline__ void gemm_stream(PG8_LAS unsigned char* lds, const Sched& S, const Epi& E) {
;     ...
;         for (int t = 0; t < nt; t += 2) {
;             const bool last = (t == nt - 2);
;             const char* a1 = cA + (size_t)(t + 1) * kstep;
;             const char* a2 = last ? nA : cA + (size_t)(t + 2) * kstep; const char* b2 = last ? nB : cB + (size_t)(t + 2) * kstep;
;             const char* a3 = a2 + kstep; const char* b3 = b2 + kstep;
;             const size_t hs2 = last ? nhs : chs;
;             const unsigned k2b = last ? nk2 : ck2;
;             const unsigned cvA = rA0 * ck2 + c20, cdv = 64u * ck2, vA2 = rA0 * k2b + c20, vB2 = rB0 * k2b + c20, dv2 = 64u * k2b;
;             PG8_LDB(B0, 0, 0); PG8_LDB(B1, 0, 1); PG8_SCHED; PG8_LDA(At, 0, 0); PG8_STAGE(PG8_SA(1, 1), a1 + chs, cvA, cdv);
;             PG8_WAIT_V(8); PG8_WAIT_L(0); PG8_BAR; PG8_MMA(0, 0, At, B0); PG8_MMA(0, 1, At, B1); PG8_BAR; PG8_SCHED;
;             PG8_LDA(At, 0, 1); PG8_STAGE(PG8_SB(0, 0), b2, vB2, dv2); PG8_STAGE(PG8_SB(0, 1), b2 + hs2, vB2, dv2); PG8_STAGE(PG8_SA(0, 0), a2, vA2, dv2);
;             PG8_WAIT_V(8); PG8_WAIT_L(0); PG8_BAR; PG8_MMA(1, 0, At, B0); PG8_MMA(1, 1, At, B1); PG8_BAR; PG8_SCHED;
;     ...
;                         for (int n = 0; n < 2; ++n) acc[a][b][m][n] = (f32x4){0.f, 0.f, 0.f, 0.f};
.LBB0_235:
	s_ashr_i32 s27, s26, 31
	s_lshl_b64 s[28:29], s[26:27], 8
	v_mov_b32_e32 v127, 0
	s_cmp_lt_i32 s61, 64
	s_cbranch_scc1 .LBB0_238
	s_ashr_i32 s6, s61, 31
	s_lshr_b32 s6, s6, 26
	s_add_i32 s6, s61, s6
	s_ashr_i32 s27, s6, 6
	s_lshl_b32 s46, s61, 1
	s_lshl_b32 s47, s26, 1
	s_add_i32 s59, s27, -2
	s_add_u32 s6, s34, 0x80
	s_addc_u32 s7, s35, 0
	v_mad_u64_u32 v[0:1], s[34:35], s46, v137, v[144:145]
	v_mov_b32_e32 v1, v179
	v_lshl_add_u64 v[128:129], s[30:31], 0, v[0:1]
	v_mad_u64_u32 v[0:1], s[34:35], v164, s61, v[144:145]
	v_mov_b32_e32 v1, v179
	s_add_u32 s73, s36, 0x100
	v_lshl_add_u64 v[130:131], s[30:31], 0, v[0:1]
	s_addc_u32 s94, s37, 0
	s_mov_b32 vcc_lo, 0
	s_cmp_eq_u32 s59, vcc_lo
	s_cselect_b64 s[36:37], -1, 0
	s_add_i32 vcc_lo, vcc_lo, 2
	s_add_u32 s50, s6, 0x80
	s_addc_u32 s51, s7, 0
	s_and_b64 s[34:35], s[36:37], exec
	s_cselect_b32 s35, s23, s51
	s_cselect_b32 s34, s22, s50
	s_cselect_b32 s58, s47, s46
	s_cselect_b32 s61, s29, s31
	s_cselect_b32 vcc_hi, s28, s30
	s_add_i32 s96, 0, 0x10000
	v_mad_u64_u32 v[174:175], s[50:51], s58, v139, v[136:137]
	s_and_b64 s[36:37], s[36:37], exec
	v_mad_u64_u32 v[224:225], s[50:51], s58, v137, v[136:137]
	s_cselect_b32 s37, s25, s94
	s_cselect_b32 s36, s24, s73
	s_add_i32 s50, 0, 0x14000
	v_add_u32_e32 v154, s96, v162
	v_add_u32_e32 v175, s50, v162
	ds_read_b128 v[132:135], v154
	ds_read_b128 v[146:149], v154 offset:1024
	ds_read_b128 v[150:153], v154 offset:2048
	ds_read_b128 v[154:157], v154 offset:3072
	ds_read_b128 v[158:161], v175
	ds_read_b128 v[166:169], v175 offset:1024
	ds_read_b128 v[170:173], v175 offset:2048
	ds_read_b128 v[180:183], v175 offset:3072
	v_lshl_add_u64 v[230:231], s[6:7], 0, v[128:129]
	s_add_i32 m0, s66, 0xc000
	ds_read_b128 v[192:195], v165
	ds_read_b128 v[196:199], v165 offset:1024
	ds_read_b128 v[200:203], v165 offset:2048
	ds_read_b128 v[204:207], v165 offset:3072
	ds_read_b128 v[208:211], v165 offset:4096
	ds_read_b128 v[212:215], v165 offset:5120
	ds_read_b128 v[216:219], v165 offset:6144
	ds_read_b128 v[220:223], v165 offset:7168
	global_load_lds_dwordx4 v[230:231], off
	v_lshl_add_u64 v[230:231], s[6:7], 0, v[130:131]
	s_add_i32 m0, s66, 0xe000
	s_nop 0
	global_load_lds_dwordx4 v[230:231], off
	s_waitcnt vmcnt(8)
	s_waitcnt lgkmcnt(0)
	s_barrier
	s_setprio 1
	s_waitcnt lgkmcnt(0)
	v_mfma_f32_16x16x32_bf16 v[124:127], v[132:135], v[192:195], 0
	v_mfma_f32_16x16x32_bf16 v[120:123], v[150:153], v[192:195], 0
	v_mfma_f32_16x16x32_bf16 v[108:111], v[132:135], v[200:203], 0
	v_mfma_f32_16x16x32_bf16 v[104:107], v[150:153], v[200:203], 0
	v_mfma_f32_16x16x32_bf16 v[92:95], v[132:135], v[208:211], 0
	v_mfma_f32_16x16x32_bf16 v[88:91], v[150:153], v[208:211], 0
	v_mfma_f32_16x16x32_bf16 v[76:79], v[132:135], v[216:219], 0
	v_mfma_f32_16x16x32_bf16 v[72:75], v[150:153], v[216:219], 0
	v_mfma_f32_16x16x32_bf16 v[124:127], v[146:149], v[196:199], v[124:127]
	v_mfma_f32_16x16x32_bf16 v[120:123], v[154:157], v[196:199], v[120:123]
	v_mfma_f32_16x16x32_bf16 v[108:111], v[146:149], v[204:207], v[108:111]
	v_mfma_f32_16x16x32_bf16 v[104:107], v[154:157], v[204:207], v[104:107]
	v_mfma_f32_16x16x32_bf16 v[92:95], v[146:149], v[212:215], v[92:95]
	v_mfma_f32_16x16x32_bf16 v[88:91], v[154:157], v[212:215], v[88:91]
	v_mfma_f32_16x16x32_bf16 v[76:79], v[146:149], v[220:223], v[76:79]
	v_mfma_f32_16x16x32_bf16 v[72:75], v[154:157], v[220:223], v[72:75]
	s_setprio 0
	s_setprio 1
	v_mfma_f32_16x16x32_bf16 v[116:119], v[158:161], v[192:195], 0
	v_mfma_f32_16x16x32_bf16 v[112:115], v[170:173], v[192:195], 0
	v_mfma_f32_16x16x32_bf16 v[100:103], v[158:161], v[200:203], 0
	v_mfma_f32_16x16x32_bf16 v[96:99], v[170:173], v[200:203], 0
	v_mfma_f32_16x16x32_bf16 v[84:87], v[158:161], v[208:211], 0
	v_mfma_f32_16x16x32_bf16 v[80:83], v[170:173], v[208:211], 0
	v_mfma_f32_16x16x32_bf16 v[68:71], v[158:161], v[216:219], 0
	v_mfma_f32_16x16x32_bf16 v[64:67], v[170:173], v[216:219], 0
	v_mfma_f32_16x16x32_bf16 v[116:119], v[166:169], v[196:199], v[116:119]
	v_mfma_f32_16x16x32_bf16 v[112:115], v[180:183], v[196:199], v[112:115]
	v_mfma_f32_16x16x32_bf16 v[100:103], v[166:169], v[204:207], v[100:103]
	v_mfma_f32_16x16x32_bf16 v[96:99], v[180:183], v[204:207], v[96:99]
	v_mfma_f32_16x16x32_bf16 v[84:87], v[166:169], v[212:215], v[84:87]
	v_mfma_f32_16x16x32_bf16 v[80:83], v[180:183], v[212:215], v[80:83]
	v_mfma_f32_16x16x32_bf16 v[68:71], v[166:169], v[220:223], v[68:71]
	v_mfma_f32_16x16x32_bf16 v[64:67], v[180:183], v[220:223], v[64:67]
	s_setprio 0
	s_barrier
	s_lshl_b32 s51, s58, 6
	s_add_i32 s58, s96, s65
	s_mov_b32 m0, s58
	ds_read_b128 v[192:195], v165 offset:16384
	ds_read_b128 v[196:199], v165 offset:17408
	ds_read_b128 v[200:203], v165 offset:18432
	ds_read_b128 v[204:207], v165 offset:19456
	ds_read_b128 v[208:211], v165 offset:20480
	ds_read_b128 v[212:215], v165 offset:21504
	ds_read_b128 v[216:219], v165 offset:22528
	ds_read_b128 v[220:223], v165 offset:23552
	v_mov_b32_e32 v175, v179
	global_load_lds_dwordx4 v174, s[36:37]
	v_add_u32_e32 v178, s51, v174
	s_add_i32 m0, s58, 0x2000
	v_lshl_add_u64 v[230:231], s[36:37], 0, v[174:175]
	v_lshl_add_u64 v[232:233], s[36:37], 0, v[178:179]
	global_load_lds_dwordx4 v178, s[36:37]
	s_add_u32 s36, s36, vcc_hi
	s_addc_u32 s37, s37, s61
	s_add_i32 s50, s50, s65
	s_mov_b32 m0, s50
	v_lshl_add_u64 v[234:235], s[36:37], 0, v[174:175]
	global_load_lds_dwordx4 v174, s[36:37]
	s_add_i32 m0, s50, 0x2000
	v_lshl_add_u64 v[174:175], s[36:37], 0, v[178:179]
	global_load_lds_dwordx4 v178, s[36:37]
	s_mov_b32 m0, s66
	v_add_u32_e32 v178, s51, v224
	global_load_lds_dwordx4 v224, s[34:35]
	s_mov_b32 m0, s67
	v_mov_b32_e32 v225, v179
	global_load_lds_dwordx4 v178, s[34:35]
	s_waitcnt vmcnt(8)
	s_waitcnt lgkmcnt(0)
	v_lshl_add_u64 v[236:237], s[34:35], 0, v[224:225]
	v_lshl_add_u64 v[238:239], s[34:35], 0, v[178:179]
	s_barrier
; #define PG8_STAGE(bufoff, gbase, v0, dv) do { _Pragma("unroll") for (int _i = 0; _i < 2; ++_i) \
;         __builtin_amdgcn_global_load_lds((const unsigned*)((const char*)(gbase) + ((v0) + (unsigned)_i * (dv))), (PG8_LAS unsigned*)(lds + (bufoff) + ldsw + _i * 8192), 16, 0, 0); } while (0)
; #define PG8_LDA(dst, b, h) do { _Pragma("unroll") for (int m = 0; m < 4; ++m) _Pragma("unroll") for (int k = 0; k < 2; ++k) dst[m][k] = *(const PG8_LAS bf16x8*)(lds + PG8_SA(b, h) + aoff + m * 2048 + k * 1024); } while (0)
; #define PG8_LDB(dst, b, h) do { _Pragma("unroll") for (int n = 0; n < 2; ++n) _Pragma("unroll") for (int k = 0; k < 2; ++k) dst[n][k] = *(const PG8_LAS bf16x8*)(lds + PG8_SB(b, h) + boff + n * 2048 + k * 1024); } while (0)
; #define PG8_MMA(ai, bj, At, Bt) do { __builtin_amdgcn_s_setprio(1); _Pragma("unroll") for (int m = 0; m < 4; ++m) _Pragma("unroll") for (int n = 0; n < 2; ++n) _Pragma("unroll") for (int k = 0; k < 2; ++k) \
;         acc[ai][bj][m][n] = __builtin_amdgcn_mfma_f32_16x16x32_bf16(Bt[n][k], At[m][k], acc[ai][bj][m][n], 0, 0, 0); __builtin_amdgcn_s_setprio(0); } while (0)
; #define PG8_WAIT_V(n) asm volatile("s_waitcnt vmcnt(" #n ")" ::: "memory")
; #define PG8_WAIT_L(n) asm volatile("s_waitcnt lgkmcnt(" #n ")" ::: "memory")
; #define PG8_BAR __builtin_amdgcn_s_barrier()
; #define PG8_SCHED __builtin_amdgcn_sched_barrier(0)
; template <class Epi, class Sched, bool MERGE>
; __device__ __forceinline__ void gemm_stream(PG8_LAS unsigned char* lds, const Sched& S, const Epi& E) {
;     ...
;             PG8_WAIT_V(8); PG8_WAIT_L(0); PG8_BAR; PG8_MMA(1, 0, At, B0); PG8_MMA(1, 1, At, B1); PG8_BAR; PG8_SCHED;
;             PG8_LDB(B0, 1, 0); PG8_LDB(B1, 1, 1); PG8_SCHED; PG8_LDA(At, 1, 0); PG8_STAGE(PG8_SA(0, 1), a2 + hs2, vA2, dv2);
;             PG8_WAIT_V(8); PG8_WAIT_L(0); PG8_BAR; PG8_MMA(0, 0, At, B0); PG8_MMA(0, 1, At, B1); PG8_BAR; PG8_SCHED;
;             PG8_LDA(At, 1, 1); PG8_STAGE(PG8_SB(1, 0), b3, vB2, dv2); PG8_STAGE(PG8_SB(1, 1), b3 + hs2, vB2, dv2); PG8_STAGE(PG8_SA(1, 0), a3, vA2, dv2);
;             PG8_WAIT_V(8); PG8_WAIT_L(0); PG8_BAR; PG8_MMA(1, 0, At, B0); PG8_MMA(1, 1, At, B1); PG8_BAR; PG8_SCHED;
	s_setprio 1
	s_waitcnt lgkmcnt(0)
	v_mfma_f32_16x16x32_bf16 v[60:63], v[132:135], v[192:195], 0
	v_mfma_f32_16x16x32_bf16 v[56:59], v[150:153], v[192:195], 0
	v_mfma_f32_16x16x32_bf16 v[44:47], v[132:135], v[200:203], 0
	v_mfma_f32_16x16x32_bf16 v[40:43], v[150:153], v[200:203], 0
	v_mfma_f32_16x16x32_bf16 v[28:31], v[132:135], v[208:211], 0
	v_mfma_f32_16x16x32_bf16 v[24:27], v[150:153], v[208:211], 0
	v_mfma_f32_16x16x32_bf16 v[12:15], v[132:135], v[216:219], 0
	v_mfma_f32_16x16x32_bf16 v[8:11], v[150:153], v[216:219], 0
	v_mfma_f32_16x16x32_bf16 v[60:63], v[146:149], v[196:199], v[60:63]
	v_mfma_f32_16x16x32_bf16 v[56:59], v[154:157], v[196:199], v[56:59]
	v_mfma_f32_16x16x32_bf16 v[44:47], v[146:149], v[204:207], v[44:47]
	v_mfma_f32_16x16x32_bf16 v[40:43], v[154:157], v[204:207], v[40:43]
	v_mfma_f32_16x16x32_bf16 v[28:31], v[146:149], v[212:215], v[28:31]
	v_mfma_f32_16x16x32_bf16 v[24:27], v[154:157], v[212:215], v[24:27]
	v_mfma_f32_16x16x32_bf16 v[12:15], v[146:149], v[220:223], v[12:15]
	v_mfma_f32_16x16x32_bf16 v[8:11], v[154:157], v[220:223], v[8:11]
	s_setprio 0
	s_setprio 1
	v_mfma_f32_16x16x32_bf16 v[52:55], v[158:161], v[192:195], 0
	v_mfma_f32_16x16x32_bf16 v[48:51], v[170:173], v[192:195], 0
	v_mfma_f32_16x16x32_bf16 v[36:39], v[158:161], v[200:203], 0
	v_mfma_f32_16x16x32_bf16 v[32:35], v[170:173], v[200:203], 0
	v_mfma_f32_16x16x32_bf16 v[20:23], v[158:161], v[208:211], 0
	v_mfma_f32_16x16x32_bf16 v[16:19], v[170:173], v[208:211], 0
	v_mfma_f32_16x16x32_bf16 v[4:7], v[158:161], v[216:219], 0
	v_mfma_f32_16x16x32_bf16 v[0:3], v[170:173], v[216:219], 0
	v_mfma_f32_16x16x32_bf16 v[52:55], v[166:169], v[196:199], v[52:55]
	v_mfma_f32_16x16x32_bf16 v[48:51], v[180:183], v[196:199], v[48:51]
	v_mfma_f32_16x16x32_bf16 v[36:39], v[166:169], v[204:207], v[36:39]
	v_mfma_f32_16x16x32_bf16 v[32:35], v[180:183], v[204:207], v[32:35]
	v_mfma_f32_16x16x32_bf16 v[20:23], v[166:169], v[212:215], v[20:23]
	v_mfma_f32_16x16x32_bf16 v[16:19], v[180:183], v[212:215], v[16:19]
	v_mfma_f32_16x16x32_bf16 v[4:7], v[166:169], v[220:223], v[4:7]
	v_mfma_f32_16x16x32_bf16 v[0:3], v[180:183], v[220:223], v[0:3]
	s_setprio 0
	s_barrier
	s_add_i32 s36, 0, 0x18000
	s_add_i32 s37, 0, 0x1c000
	v_add_u32_e32 v154, s36, v162
	v_add_u32_e32 v180, s37, v162
	ds_read_b128 v[132:135], v154
	ds_read_b128 v[146:149], v154 offset:1024
	ds_read_b128 v[150:153], v154 offset:2048
	ds_read_b128 v[154:157], v154 offset:3072
	ds_read_b128 v[158:161], v180
	ds_read_b128 v[166:169], v180 offset:1024
	ds_read_b128 v[170:173], v180 offset:2048
	ds_read_b128 v[180:183], v180 offset:3072
	s_add_u32 s34, s34, vcc_hi
	s_addc_u32 s35, s35, s61
	s_mov_b32 m0, s68
	ds_read_b128 v[192:195], v165 offset:32768
	ds_read_b128 v[196:199], v165 offset:33792
	ds_read_b128 v[200:203], v165 offset:34816
	ds_read_b128 v[204:207], v165 offset:35840
	ds_read_b128 v[208:211], v165 offset:36864
	ds_read_b128 v[212:215], v165 offset:37888
	ds_read_b128 v[216:219], v165 offset:38912
	ds_read_b128 v[220:223], v165 offset:39936
	global_load_lds_dwordx4 v224, s[34:35]
	s_mov_b32 m0, s69
	s_nop 0
	global_load_lds_dwordx4 v178, s[34:35]
	s_waitcnt vmcnt(8)
	s_waitcnt lgkmcnt(0)
	s_barrier
	s_setprio 1
	s_waitcnt lgkmcnt(0)
	v_mfma_f32_16x16x32_bf16 v[124:127], v[132:135], v[192:195], v[124:127]
	v_mfma_f32_16x16x32_bf16 v[120:123], v[150:153], v[192:195], v[120:123]
	v_mfma_f32_16x16x32_bf16 v[108:111], v[132:135], v[200:203], v[108:111]
	v_mfma_f32_16x16x32_bf16 v[104:107], v[150:153], v[200:203], v[104:107]
	v_mfma_f32_16x16x32_bf16 v[92:95], v[132:135], v[208:211], v[92:95]
	v_mfma_f32_16x16x32_bf16 v[88:91], v[150:153], v[208:211], v[88:91]
	v_mfma_f32_16x16x32_bf16 v[76:79], v[132:135], v[216:219], v[76:79]
	v_mfma_f32_16x16x32_bf16 v[72:75], v[150:153], v[216:219], v[72:75]
	v_mfma_f32_16x16x32_bf16 v[124:127], v[146:149], v[196:199], v[124:127]
	v_mfma_f32_16x16x32_bf16 v[120:123], v[154:157], v[196:199], v[120:123]
	v_mfma_f32_16x16x32_bf16 v[108:111], v[146:149], v[204:207], v[108:111]
	v_mfma_f32_16x16x32_bf16 v[104:107], v[154:157], v[204:207], v[104:107]
	v_mfma_f32_16x16x32_bf16 v[92:95], v[146:149], v[212:215], v[92:95]
	v_mfma_f32_16x16x32_bf16 v[88:91], v[154:157], v[212:215], v[88:91]
	v_mfma_f32_16x16x32_bf16 v[76:79], v[146:149], v[220:223], v[76:79]
	v_mfma_f32_16x16x32_bf16 v[72:75], v[154:157], v[220:223], v[72:75]
	s_setprio 0
	s_setprio 1
	v_mfma_f32_16x16x32_bf16 v[116:119], v[158:161], v[192:195], v[116:119]
	v_mfma_f32_16x16x32_bf16 v[112:115], v[170:173], v[192:195], v[112:115]
	v_mfma_f32_16x16x32_bf16 v[100:103], v[158:161], v[200:203], v[100:103]
	v_mfma_f32_16x16x32_bf16 v[96:99], v[170:173], v[200:203], v[96:99]
	v_mfma_f32_16x16x32_bf16 v[84:87], v[158:161], v[208:211], v[84:87]
	v_mfma_f32_16x16x32_bf16 v[80:83], v[170:173], v[208:211], v[80:83]
	v_mfma_f32_16x16x32_bf16 v[68:71], v[158:161], v[216:219], v[68:71]
	v_mfma_f32_16x16x32_bf16 v[64:67], v[170:173], v[216:219], v[64:67]
	v_mfma_f32_16x16x32_bf16 v[116:119], v[166:169], v[196:199], v[116:119]
	v_mfma_f32_16x16x32_bf16 v[112:115], v[180:183], v[196:199], v[112:115]
	v_mfma_f32_16x16x32_bf16 v[100:103], v[166:169], v[204:207], v[100:103]
	v_mfma_f32_16x16x32_bf16 v[96:99], v[180:183], v[204:207], v[96:99]
	v_mfma_f32_16x16x32_bf16 v[84:87], v[166:169], v[212:215], v[84:87]
	v_mfma_f32_16x16x32_bf16 v[80:83], v[180:183], v[212:215], v[80:83]
	v_mfma_f32_16x16x32_bf16 v[68:71], v[166:169], v[220:223], v[68:71]
	v_mfma_f32_16x16x32_bf16 v[64:67], v[180:183], v[220:223], v[64:67]
	s_setprio 0
	s_barrier
; #define PG8_STAGE(bufoff, gbase, v0, dv) do { _Pragma("unroll") for (int _i = 0; _i < 2; ++_i) \
;         __builtin_amdgcn_global_load_lds((const unsigned*)((const char*)(gbase) + ((v0) + (unsigned)_i * (dv))), (PG8_LAS unsigned*)(lds + (bufoff) + ldsw + _i * 8192), 16, 0, 0); } while (0)
; #define PG8_LDA(dst, b, h) do { _Pragma("unroll") for (int m = 0; m < 4; ++m) _Pragma("unroll") for (int k = 0; k < 2; ++k) dst[m][k] = *(const PG8_LAS bf16x8*)(lds + PG8_SA(b, h) + aoff + m * 2048 + k * 1024); } while (0)
; #define PG8_MMA(ai, bj, At, Bt) do { __builtin_amdgcn_s_setprio(1); _Pragma("unroll") for (int m = 0; m < 4; ++m) _Pragma("unroll") for (int n = 0; n < 2; ++n) _Pragma("unroll") for (int k = 0; k < 2; ++k) \
;         acc[ai][bj][m][n] = __builtin_amdgcn_mfma_f32_16x16x32_bf16(Bt[n][k], At[m][k], acc[ai][bj][m][n], 0, 0, 0); __builtin_amdgcn_s_setprio(0); } while (0)
; #define PG8_WAIT_V(n) asm volatile("s_waitcnt vmcnt(" #n ")" ::: "memory")
; #define PG8_WAIT_L(n) asm volatile("s_waitcnt lgkmcnt(" #n ")" ::: "memory")
; #define PG8_BAR __builtin_amdgcn_s_barrier()
; #define PG8_SCHED __builtin_amdgcn_sched_barrier(0)
; template <class Epi, class Sched, bool MERGE>
; __device__ __forceinline__ void gemm_stream(PG8_LAS unsigned char* lds, const Sched& S, const Epi& E) {
;     ...
;         for (int t = 0; t < nt; t += 2) {
;     ...
;             PG8_LDA(At, 1, 1); PG8_STAGE(PG8_SB(1, 0), b3, vB2, dv2); PG8_STAGE(PG8_SB(1, 1), b3 + hs2, vB2, dv2); PG8_STAGE(PG8_SA(1, 0), a3, vA2, dv2);
;             PG8_WAIT_V(8); PG8_WAIT_L(0); PG8_BAR; PG8_MMA(1, 0, At, B0); PG8_MMA(1, 1, At, B1); PG8_BAR; PG8_SCHED;
	s_add_i32 s34, s36, s65
	v_lshl_add_u64 v[224:225], v[230:231], 0, s[48:49]
	s_mov_b32 m0, s34
	ds_read_b128 v[192:195], v165 offset:49152
	ds_read_b128 v[196:199], v165 offset:50176
	ds_read_b128 v[200:203], v165 offset:51200
	ds_read_b128 v[204:207], v165 offset:52224
	ds_read_b128 v[208:211], v165 offset:53248
	ds_read_b128 v[212:215], v165 offset:54272
	ds_read_b128 v[216:219], v165 offset:55296
	ds_read_b128 v[220:223], v165 offset:56320
	global_load_lds_dwordx4 v[224:225], off
	v_lshl_add_u64 v[224:225], v[232:233], 0, s[48:49]
	s_add_i32 m0, s34, 0x2000
	s_add_i32 s34, s37, s65
	global_load_lds_dwordx4 v[224:225], off
	v_lshl_add_u64 v[224:225], v[234:235], 0, s[48:49]
	s_mov_b32 m0, s34
	v_lshl_add_u64 v[174:175], v[174:175], 0, s[48:49]
	global_load_lds_dwordx4 v[224:225], off
	s_add_i32 m0, s34, 0x2000
	s_nop 0
	global_load_lds_dwordx4 v[174:175], off
	v_lshl_add_u64 v[174:175], v[236:237], 0, s[48:49]
	s_mov_b32 m0, s71
	s_nop 0
	global_load_lds_dwordx4 v[174:175], off
	v_lshl_add_u64 v[174:175], v[238:239], 0, s[48:49]
	s_mov_b32 m0, s74
	s_nop 0
	global_load_lds_dwordx4 v[174:175], off
	s_waitcnt vmcnt(8)
	s_waitcnt lgkmcnt(0)
	s_barrier
	s_setprio 1
	s_waitcnt lgkmcnt(0)
	v_mfma_f32_16x16x32_bf16 v[60:63], v[132:135], v[192:195], v[60:63]
	v_mfma_f32_16x16x32_bf16 v[56:59], v[150:153], v[192:195], v[56:59]
	v_mfma_f32_16x16x32_bf16 v[44:47], v[132:135], v[200:203], v[44:47]
	v_mfma_f32_16x16x32_bf16 v[40:43], v[150:153], v[200:203], v[40:43]
	v_mfma_f32_16x16x32_bf16 v[28:31], v[132:135], v[208:211], v[28:31]
	v_mfma_f32_16x16x32_bf16 v[24:27], v[150:153], v[208:211], v[24:27]
	v_mfma_f32_16x16x32_bf16 v[12:15], v[132:135], v[216:219], v[12:15]
	v_mfma_f32_16x16x32_bf16 v[8:11], v[150:153], v[216:219], v[8:11]
	v_mfma_f32_16x16x32_bf16 v[60:63], v[146:149], v[196:199], v[60:63]
	v_mfma_f32_16x16x32_bf16 v[56:59], v[154:157], v[196:199], v[56:59]
	v_mfma_f32_16x16x32_bf16 v[44:47], v[146:149], v[204:207], v[44:47]
	v_mfma_f32_16x16x32_bf16 v[40:43], v[154:157], v[204:207], v[40:43]
	v_mfma_f32_16x16x32_bf16 v[28:31], v[146:149], v[212:215], v[28:31]
	v_mfma_f32_16x16x32_bf16 v[24:27], v[154:157], v[212:215], v[24:27]
	v_mfma_f32_16x16x32_bf16 v[12:15], v[146:149], v[220:223], v[12:15]
	v_mfma_f32_16x16x32_bf16 v[8:11], v[154:157], v[220:223], v[8:11]
	s_setprio 0
	s_setprio 1
	v_mfma_f32_16x16x32_bf16 v[52:55], v[158:161], v[192:195], v[52:55]
	v_mfma_f32_16x16x32_bf16 v[48:51], v[170:173], v[192:195], v[48:51]
	v_mfma_f32_16x16x32_bf16 v[36:39], v[158:161], v[200:203], v[36:39]
	v_mfma_f32_16x16x32_bf16 v[32:35], v[170:173], v[200:203], v[32:35]
	v_mfma_f32_16x16x32_bf16 v[20:23], v[158:161], v[208:211], v[20:23]
	v_mfma_f32_16x16x32_bf16 v[16:19], v[170:173], v[208:211], v[16:19]
	v_mfma_f32_16x16x32_bf16 v[4:7], v[158:161], v[216:219], v[4:7]
	v_mfma_f32_16x16x32_bf16 v[0:3], v[170:173], v[216:219], v[0:3]
	v_mfma_f32_16x16x32_bf16 v[52:55], v[166:169], v[196:199], v[52:55]
	v_mfma_f32_16x16x32_bf16 v[48:51], v[180:183], v[196:199], v[48:51]
	v_mfma_f32_16x16x32_bf16 v[36:39], v[166:169], v[204:207], v[36:39]
	v_mfma_f32_16x16x32_bf16 v[32:35], v[180:183], v[204:207], v[32:35]
	v_mfma_f32_16x16x32_bf16 v[20:23], v[166:169], v[212:215], v[20:23]
	v_mfma_f32_16x16x32_bf16 v[16:19], v[180:183], v[212:215], v[16:19]
	v_mfma_f32_16x16x32_bf16 v[4:7], v[166:169], v[220:223], v[4:7]
	v_mfma_f32_16x16x32_bf16 v[0:3], v[180:183], v[220:223], v[0:3]
	s_setprio 0
	s_barrier
	s_add_u32 s6, s6, 0x100
	s_addc_u32 s7, s7, 0
	s_add_u32 s73, s73, 0x100
	s_addc_u32 s94, s94, 0
	s_cmp_ge_i32 vcc_lo, s27
	s_cbranch_scc1 .LBB0_238
